# MLP-up epilogue: lane-paired (v_permlane16_swap) 16-byte fp8 stores instead of two 8-byte ones, no max(x,x); on top of conv + copy-path changes
# speedup vs baseline: 1.0027x; 1.0027x over previous
.LBB0_1064:
	s_nop 7
	s_nop 7
	v_lshl_add_u32 v2, s46, 8, v188
	v_ashrrev_i32_e32 v3, 31, v2
	v_lshl_or_b32 v0, s44, 8, v190
	v_lshlrev_b64 v[4:5], 13, v[2:3]
	v_ashrrev_i32_e32 v1, 31, v0
	v_lshl_add_u64 v[4:5], s[50:51], 0, v[4:5]
	v_lshl_add_u64 v[4:5], v[4:5], 0, v[0:1]
	v_bfe_u32 v0, v184, 4, 1
	v_mul_u32_u24_e32 v0, 0x78, v0
	v_mov_b32_e32 v1, 0
	v_lshl_add_u64 v[4:5], v[4:5], 0, v[0:1]
	s_mov_b64 s[100:101], 0x20000
	s_and_b64 vcc, exec, s[6:7]
	v_max_f32_e32 v12, 0, v156
	v_max_f32_e32 v16, 0, v152
	v_max_f32_e32 v13, 0, v157
	v_max_f32_e32 v17, 0, v153
	v_max_f32_e32 v14, 0, v158
	v_max_f32_e32 v18, 0, v154
	v_max_f32_e32 v15, 0, v159
	v_max_f32_e32 v19, 0, v155
	v_mul_f32_e32 v12, v12, v12
	v_mul_f32_e32 v16, v16, v16
	v_mul_f32_e32 v13, v13, v13
	v_mul_f32_e32 v17, v17, v17
	v_mul_f32_e32 v14, v14, v14
	v_mul_f32_e32 v18, v18, v18
	v_mul_f32_e32 v15, v15, v15
	v_mul_f32_e32 v19, v19, v19
	v_cvt_pk_fp8_f32 v8, v12, v13
	v_cvt_pk_fp8_f32 v9, v16, v17
	v_cvt_pk_fp8_f32 v8, v14, v15 op_sel:[0,0,1]
	v_cvt_pk_fp8_f32 v9, v18, v19 op_sel:[0,0,1]
	v_max_f32_e32 v12, 0, v148
	v_max_f32_e32 v16, 0, v144
	v_max_f32_e32 v13, 0, v149
	v_max_f32_e32 v17, 0, v145
	v_max_f32_e32 v14, 0, v150
	v_max_f32_e32 v18, 0, v146
	v_max_f32_e32 v15, 0, v151
	v_max_f32_e32 v19, 0, v147
	v_mul_f32_e32 v12, v12, v12
	v_mul_f32_e32 v16, v16, v16
	v_mul_f32_e32 v13, v13, v13
	v_mul_f32_e32 v17, v17, v17
	v_mul_f32_e32 v14, v14, v14
	v_mul_f32_e32 v18, v18, v18
	v_mul_f32_e32 v15, v15, v15
	v_mul_f32_e32 v19, v19, v19
	v_cvt_pk_fp8_f32 v10, v12, v13
	v_cvt_pk_fp8_f32 v11, v16, v17
	v_cvt_pk_fp8_f32 v10, v14, v15 op_sel:[0,0,1]
	v_cvt_pk_fp8_f32 v11, v18, v19 op_sel:[0,0,1]
	s_nop 1
	v_permlane16_swap_b32_e32 v8, v10
	v_permlane16_swap_b32_e32 v9, v11
	s_cbranch_vccnz .Lep8_sc_0
	global_store_dwordx4 v[4:5], v[8:11], off
	s_branch .Lep8_dn_0
.Lep8_sc_0:
	global_store_dwordx4 v[4:5], v[8:11], off sc1
	s_nop 1
.Lep8_dn_0:
	v_lshl_add_u64 v[4:5], v[4:5], 0, s[100:101]
	v_max_f32_e32 v12, 0, v140
	v_max_f32_e32 v16, 0, v136
	v_max_f32_e32 v13, 0, v141
	v_max_f32_e32 v17, 0, v137
	v_max_f32_e32 v14, 0, v142
	v_max_f32_e32 v18, 0, v138
	v_max_f32_e32 v15, 0, v143
	v_max_f32_e32 v19, 0, v139
	v_mul_f32_e32 v12, v12, v12
	v_mul_f32_e32 v16, v16, v16
	v_mul_f32_e32 v13, v13, v13
	v_mul_f32_e32 v17, v17, v17
	v_mul_f32_e32 v14, v14, v14
	v_mul_f32_e32 v18, v18, v18
	v_mul_f32_e32 v15, v15, v15
	v_mul_f32_e32 v19, v19, v19
	v_cvt_pk_fp8_f32 v8, v12, v13
	v_cvt_pk_fp8_f32 v9, v16, v17
	v_cvt_pk_fp8_f32 v8, v14, v15 op_sel:[0,0,1]
	v_cvt_pk_fp8_f32 v9, v18, v19 op_sel:[0,0,1]
	v_max_f32_e32 v12, 0, v132
	v_max_f32_e32 v16, 0, v128
	v_max_f32_e32 v13, 0, v133
	v_max_f32_e32 v17, 0, v129
	v_max_f32_e32 v14, 0, v134
	v_max_f32_e32 v18, 0, v130
	v_max_f32_e32 v15, 0, v135
	v_max_f32_e32 v19, 0, v131
	v_mul_f32_e32 v12, v12, v12
	v_mul_f32_e32 v16, v16, v16
	v_mul_f32_e32 v13, v13, v13
	v_mul_f32_e32 v17, v17, v17
	v_mul_f32_e32 v14, v14, v14
	v_mul_f32_e32 v18, v18, v18
	v_mul_f32_e32 v15, v15, v15
	v_mul_f32_e32 v19, v19, v19
	v_cvt_pk_fp8_f32 v10, v12, v13
	v_cvt_pk_fp8_f32 v11, v16, v17
	v_cvt_pk_fp8_f32 v10, v14, v15 op_sel:[0,0,1]
	v_cvt_pk_fp8_f32 v11, v18, v19 op_sel:[0,0,1]
	s_nop 1
	v_permlane16_swap_b32_e32 v8, v10
	v_permlane16_swap_b32_e32 v9, v11
	s_cbranch_vccnz .Lep8_sc_1
	global_store_dwordx4 v[4:5], v[8:11], off
	s_branch .Lep8_dn_1

.Lep8_dn_1:
	v_lshl_add_u64 v[4:5], v[4:5], 0, s[100:101]
	v_max_f32_e32 v12, 0, v124
	v_max_f32_e32 v16, 0, v120
	v_max_f32_e32 v13, 0, v125
	v_max_f32_e32 v17, 0, v121
	v_max_f32_e32 v14, 0, v126
	v_max_f32_e32 v18, 0, v122
	v_max_f32_e32 v15, 0, v127
	v_max_f32_e32 v19, 0, v123
	v_mul_f32_e32 v12, v12, v12
	v_mul_f32_e32 v16, v16, v16
	v_mul_f32_e32 v13, v13, v13
	v_mul_f32_e32 v17, v17, v17
	v_mul_f32_e32 v14, v14, v14
	v_mul_f32_e32 v18, v18, v18
	v_mul_f32_e32 v15, v15, v15
	v_mul_f32_e32 v19, v19, v19
	v_cvt_pk_fp8_f32 v8, v12, v13
	v_cvt_pk_fp8_f32 v9, v16, v17
	v_cvt_pk_fp8_f32 v8, v14, v15 op_sel:[0,0,1]
	v_cvt_pk_fp8_f32 v9, v18, v19 op_sel:[0,0,1]
	v_max_f32_e32 v12, 0, v116
	v_max_f32_e32 v16, 0, v112
	v_max_f32_e32 v13, 0, v117
	v_max_f32_e32 v17, 0, v113
	v_max_f32_e32 v14, 0, v118
	v_max_f32_e32 v18, 0, v114
	v_max_f32_e32 v15, 0, v119
	v_max_f32_e32 v19, 0, v115
	v_mul_f32_e32 v12, v12, v12
	v_mul_f32_e32 v16, v16, v16
	v_mul_f32_e32 v13, v13, v13
	v_mul_f32_e32 v17, v17, v17
	v_mul_f32_e32 v14, v14, v14
	v_mul_f32_e32 v18, v18, v18
	v_mul_f32_e32 v15, v15, v15
	v_mul_f32_e32 v19, v19, v19
	v_cvt_pk_fp8_f32 v10, v12, v13
	v_cvt_pk_fp8_f32 v11, v16, v17
	v_cvt_pk_fp8_f32 v10, v14, v15 op_sel:[0,0,1]
	v_cvt_pk_fp8_f32 v11, v18, v19 op_sel:[0,0,1]
	s_nop 1
	v_permlane16_swap_b32_e32 v8, v10
	v_permlane16_swap_b32_e32 v9, v11
	s_cbranch_vccnz .Lep8_sc_2
	global_store_dwordx4 v[4:5], v[8:11], off
	s_branch .Lep8_dn_2

.Lep8_dn_2:
	v_lshl_add_u64 v[4:5], v[4:5], 0, s[100:101]
	v_max_f32_e32 v12, 0, v108
	v_max_f32_e32 v16, 0, v104
	v_max_f32_e32 v13, 0, v109
	v_max_f32_e32 v17, 0, v105
	v_max_f32_e32 v14, 0, v110
	v_max_f32_e32 v18, 0, v106
	v_max_f32_e32 v15, 0, v111
	v_max_f32_e32 v19, 0, v107
	v_mul_f32_e32 v12, v12, v12
	v_mul_f32_e32 v16, v16, v16
	v_mul_f32_e32 v13, v13, v13
	v_mul_f32_e32 v17, v17, v17
	v_mul_f32_e32 v14, v14, v14
	v_mul_f32_e32 v18, v18, v18
	v_mul_f32_e32 v15, v15, v15
	v_mul_f32_e32 v19, v19, v19
	v_cvt_pk_fp8_f32 v8, v12, v13
	v_cvt_pk_fp8_f32 v9, v16, v17
	v_cvt_pk_fp8_f32 v8, v14, v15 op_sel:[0,0,1]
	v_cvt_pk_fp8_f32 v9, v18, v19 op_sel:[0,0,1]
	v_max_f32_e32 v12, 0, v100
	v_max_f32_e32 v16, 0, v96
	v_max_f32_e32 v13, 0, v101
	v_max_f32_e32 v17, 0, v97
	v_max_f32_e32 v14, 0, v102
	v_max_f32_e32 v18, 0, v98
	v_max_f32_e32 v15, 0, v103
	v_max_f32_e32 v19, 0, v99
	v_mul_f32_e32 v12, v12, v12
	v_mul_f32_e32 v16, v16, v16
	v_mul_f32_e32 v13, v13, v13
	v_mul_f32_e32 v17, v17, v17
	v_mul_f32_e32 v14, v14, v14
	v_mul_f32_e32 v18, v18, v18
	v_mul_f32_e32 v15, v15, v15
	v_mul_f32_e32 v19, v19, v19
	v_cvt_pk_fp8_f32 v10, v12, v13
	v_cvt_pk_fp8_f32 v11, v16, v17
	v_cvt_pk_fp8_f32 v10, v14, v15 op_sel:[0,0,1]
	v_cvt_pk_fp8_f32 v11, v18, v19 op_sel:[0,0,1]
	s_nop 1
	v_permlane16_swap_b32_e32 v8, v10
	v_permlane16_swap_b32_e32 v9, v11
	s_cbranch_vccnz .Lep8_sc_3
	global_store_dwordx4 v[4:5], v[8:11], off
	s_branch .Lep8_dn_3

.Lep8_dn_3:
	v_lshl_add_u64 v[4:5], v[4:5], 0, s[100:101]
	v_lshl_add_u64 v[4:5], v[4:5], 0, s[100:101]
	v_lshl_add_u64 v[4:5], v[4:5], 0, s[100:101]
	v_lshl_add_u64 v[4:5], v[4:5], 0, s[100:101]
	v_lshl_add_u64 v[4:5], v[4:5], 0, s[100:101]
	v_max_f32_e32 v12, 0, v92
	v_max_f32_e32 v16, 0, v88
	v_max_f32_e32 v13, 0, v93
	v_max_f32_e32 v17, 0, v89
	v_max_f32_e32 v14, 0, v94
	v_max_f32_e32 v18, 0, v90
	v_max_f32_e32 v15, 0, v95
	v_max_f32_e32 v19, 0, v91
	v_mul_f32_e32 v12, v12, v12
	v_mul_f32_e32 v16, v16, v16
	v_mul_f32_e32 v13, v13, v13
	v_mul_f32_e32 v17, v17, v17
	v_mul_f32_e32 v14, v14, v14
	v_mul_f32_e32 v18, v18, v18
	v_mul_f32_e32 v15, v15, v15
	v_mul_f32_e32 v19, v19, v19
	v_cvt_pk_fp8_f32 v8, v12, v13
	v_cvt_pk_fp8_f32 v9, v16, v17
	v_cvt_pk_fp8_f32 v8, v14, v15 op_sel:[0,0,1]
	v_cvt_pk_fp8_f32 v9, v18, v19 op_sel:[0,0,1]
	v_max_f32_e32 v12, 0, v84
	v_max_f32_e32 v16, 0, v80
	v_max_f32_e32 v13, 0, v85
	v_max_f32_e32 v17, 0, v81
	v_max_f32_e32 v14, 0, v86
	v_max_f32_e32 v18, 0, v82
	v_max_f32_e32 v15, 0, v87
	v_max_f32_e32 v19, 0, v83
	v_mul_f32_e32 v12, v12, v12
	v_mul_f32_e32 v16, v16, v16
	v_mul_f32_e32 v13, v13, v13
	v_mul_f32_e32 v17, v17, v17
	v_mul_f32_e32 v14, v14, v14
	v_mul_f32_e32 v18, v18, v18
	v_mul_f32_e32 v15, v15, v15
	v_mul_f32_e32 v19, v19, v19
	v_cvt_pk_fp8_f32 v10, v12, v13
	v_cvt_pk_fp8_f32 v11, v16, v17
	v_cvt_pk_fp8_f32 v10, v14, v15 op_sel:[0,0,1]
	v_cvt_pk_fp8_f32 v11, v18, v19 op_sel:[0,0,1]
	s_nop 1
	v_permlane16_swap_b32_e32 v8, v10
	v_permlane16_swap_b32_e32 v9, v11
	s_cbranch_vccnz .Lep8_sc_4
	global_store_dwordx4 v[4:5], v[8:11], off
	s_branch .Lep8_dn_4

.Lep8_dn_4:
	v_lshl_add_u64 v[4:5], v[4:5], 0, s[100:101]
	v_max_f32_e32 v12, 0, v76
	v_max_f32_e32 v16, 0, v72
	v_max_f32_e32 v13, 0, v77
	v_max_f32_e32 v17, 0, v73
	v_max_f32_e32 v14, 0, v78
	v_max_f32_e32 v18, 0, v74
	v_max_f32_e32 v15, 0, v79
	v_max_f32_e32 v19, 0, v75
	v_mul_f32_e32 v12, v12, v12
	v_mul_f32_e32 v16, v16, v16
	v_mul_f32_e32 v13, v13, v13
	v_mul_f32_e32 v17, v17, v17
	v_mul_f32_e32 v14, v14, v14
	v_mul_f32_e32 v18, v18, v18
	v_mul_f32_e32 v15, v15, v15
	v_mul_f32_e32 v19, v19, v19
	v_cvt_pk_fp8_f32 v8, v12, v13
	v_cvt_pk_fp8_f32 v9, v16, v17
	v_cvt_pk_fp8_f32 v8, v14, v15 op_sel:[0,0,1]
	v_cvt_pk_fp8_f32 v9, v18, v19 op_sel:[0,0,1]
	v_max_f32_e32 v12, 0, v68
	v_max_f32_e32 v16, 0, v64
	v_max_f32_e32 v13, 0, v69
	v_max_f32_e32 v17, 0, v65
	v_max_f32_e32 v14, 0, v70
	v_max_f32_e32 v18, 0, v66
	v_max_f32_e32 v15, 0, v71
	v_max_f32_e32 v19, 0, v67
	v_mul_f32_e32 v12, v12, v12
	v_mul_f32_e32 v16, v16, v16
	v_mul_f32_e32 v13, v13, v13
	v_mul_f32_e32 v17, v17, v17
	v_mul_f32_e32 v14, v14, v14
	v_mul_f32_e32 v18, v18, v18
	v_mul_f32_e32 v15, v15, v15
	v_mul_f32_e32 v19, v19, v19
	v_cvt_pk_fp8_f32 v10, v12, v13
	v_cvt_pk_fp8_f32 v11, v16, v17
	v_cvt_pk_fp8_f32 v10, v14, v15 op_sel:[0,0,1]
	v_cvt_pk_fp8_f32 v11, v18, v19 op_sel:[0,0,1]
	s_nop 1
	v_permlane16_swap_b32_e32 v8, v10
	v_permlane16_swap_b32_e32 v9, v11
	s_cbranch_vccnz .Lep8_sc_5
	global_store_dwordx4 v[4:5], v[8:11], off
	s_branch .Lep8_dn_5

.Lep8_dn_5:
	v_lshl_add_u64 v[4:5], v[4:5], 0, s[100:101]
	v_max_f32_e32 v12, 0, v60
	v_max_f32_e32 v16, 0, v56
	v_max_f32_e32 v13, 0, v61
	v_max_f32_e32 v17, 0, v57
	v_max_f32_e32 v14, 0, v62
	v_max_f32_e32 v18, 0, v58
	v_max_f32_e32 v15, 0, v63
	v_max_f32_e32 v19, 0, v59
	v_mul_f32_e32 v12, v12, v12
	v_mul_f32_e32 v16, v16, v16
	v_mul_f32_e32 v13, v13, v13
	v_mul_f32_e32 v17, v17, v17
	v_mul_f32_e32 v14, v14, v14
	v_mul_f32_e32 v18, v18, v18
	v_mul_f32_e32 v15, v15, v15
	v_mul_f32_e32 v19, v19, v19
	v_cvt_pk_fp8_f32 v8, v12, v13
	v_cvt_pk_fp8_f32 v9, v16, v17
	v_cvt_pk_fp8_f32 v8, v14, v15 op_sel:[0,0,1]
	v_cvt_pk_fp8_f32 v9, v18, v19 op_sel:[0,0,1]
	v_max_f32_e32 v12, 0, v52
	v_max_f32_e32 v16, 0, v48
	v_max_f32_e32 v13, 0, v53
	v_max_f32_e32 v17, 0, v49
	v_max_f32_e32 v14, 0, v54
	v_max_f32_e32 v18, 0, v50
	v_max_f32_e32 v15, 0, v55
	v_max_f32_e32 v19, 0, v51
	v_mul_f32_e32 v12, v12, v12
	v_mul_f32_e32 v16, v16, v16
	v_mul_f32_e32 v13, v13, v13
	v_mul_f32_e32 v17, v17, v17
	v_mul_f32_e32 v14, v14, v14
	v_mul_f32_e32 v18, v18, v18
	v_mul_f32_e32 v15, v15, v15
	v_mul_f32_e32 v19, v19, v19
	v_cvt_pk_fp8_f32 v10, v12, v13
	v_cvt_pk_fp8_f32 v11, v16, v17
	v_cvt_pk_fp8_f32 v10, v14, v15 op_sel:[0,0,1]
	v_cvt_pk_fp8_f32 v11, v18, v19 op_sel:[0,0,1]
	s_nop 1
	v_permlane16_swap_b32_e32 v8, v10
	v_permlane16_swap_b32_e32 v9, v11
	s_cbranch_vccnz .Lep8_sc_6
	global_store_dwordx4 v[4:5], v[8:11], off
	s_branch .Lep8_dn_6

.Lep8_dn_6:
	v_lshl_add_u64 v[4:5], v[4:5], 0, s[100:101]
	v_max_f32_e32 v12, 0, v44
	v_max_f32_e32 v16, 0, v40
	v_max_f32_e32 v13, 0, v45
	v_max_f32_e32 v17, 0, v41
	v_max_f32_e32 v14, 0, v46
	v_max_f32_e32 v18, 0, v42
	v_max_f32_e32 v15, 0, v47
	v_max_f32_e32 v19, 0, v43
	v_mul_f32_e32 v12, v12, v12
	v_mul_f32_e32 v16, v16, v16
	v_mul_f32_e32 v13, v13, v13
	v_mul_f32_e32 v17, v17, v17
	v_mul_f32_e32 v14, v14, v14
	v_mul_f32_e32 v18, v18, v18
	v_mul_f32_e32 v15, v15, v15
	v_mul_f32_e32 v19, v19, v19
	v_cvt_pk_fp8_f32 v8, v12, v13
	v_cvt_pk_fp8_f32 v9, v16, v17
	v_cvt_pk_fp8_f32 v8, v14, v15 op_sel:[0,0,1]
	v_cvt_pk_fp8_f32 v9, v18, v19 op_sel:[0,0,1]
	v_max_f32_e32 v12, 0, v36
	v_max_f32_e32 v16, 0, v32
	v_max_f32_e32 v13, 0, v37
	v_max_f32_e32 v17, 0, v33
	v_max_f32_e32 v14, 0, v38
	v_max_f32_e32 v18, 0, v34
	v_max_f32_e32 v15, 0, v39
	v_max_f32_e32 v19, 0, v35
	v_mul_f32_e32 v12, v12, v12
	v_mul_f32_e32 v16, v16, v16
	v_mul_f32_e32 v13, v13, v13
	v_mul_f32_e32 v17, v17, v17
	v_mul_f32_e32 v14, v14, v14
	v_mul_f32_e32 v18, v18, v18
	v_mul_f32_e32 v15, v15, v15
	v_mul_f32_e32 v19, v19, v19
	v_cvt_pk_fp8_f32 v10, v12, v13
	v_cvt_pk_fp8_f32 v11, v16, v17
	v_cvt_pk_fp8_f32 v10, v14, v15 op_sel:[0,0,1]
	v_cvt_pk_fp8_f32 v11, v18, v19 op_sel:[0,0,1]
	s_nop 1
	v_permlane16_swap_b32_e32 v8, v10
	v_permlane16_swap_b32_e32 v9, v11
	s_cbranch_vccnz .Lep8_sc_7
	global_store_dwordx4 v[4:5], v[8:11], off
	s_branch .Lep8_dn_7

.Lep8_dn_7:
.LBB0_1126:
	s_andn2_b64 vcc, exec, s[4:5]
	s_mov_b64 s[4:5], -1
	s_cbranch_vccnz .LBB0_1057
	s_branch .LBB0_1129
